# duty_on_column_tiles_5_to_20
# speedup vs baseline: 1.0124x; 1.0075x over previous
; __device__ __forceinline__ void p0_load4(const Args& a, int m0, int NGW, int lane, f32x4 (&v)[4][4]) {
; #pragma unroll
;     for (int u = 0; u < 4; ++u) { const int m = min(m0 + u * NGW, T - 1);
;         const float* xrow = m < TP ? a.in[0] + (size_t)m * 1024 : a.in[1] + (size_t)(m - TP) * 1024;
;         const f32x4* xr = (const f32x4*)xrow + lane;
; #pragma unroll
;         for (int j = 0; j < 4; ++j) v[u][j] = xr[64 * j]; }
; }
.Lax_noep:
	s_lshr_b32 s100, s8, 5
	s_bfe_u32 s98, s8, 0x20003
	s_sub_i32 s101, s38, 5
	s_cmp_lt_u32 s101, 16
	s_cbranch_scc0 .Lax_noduty
	s_lshl_b32 s101, s101, 2
	s_add_i32 s98, s98, s101
	s_cmp_lt_u32 s100, 4
	s_cbranch_scc0 .Lax_noduty
	s_lshl_b32 s100, s100, 2
	s_lshr_b32 s101, s98, 4
	s_add_i32 s100, s100, s101
	s_add_i32 s100, s100, 8
	s_lshl_b32 s100, s100, 3
	s_and_b32 s101, s8, 7
	s_or_b32 s100, s100, s101
	s_lshl_b32 s100, s100, 8
	s_and_b32 s101, s98, 15
	s_lshl_b32 s101, s101, 4
	s_add_i32 s98, s100, s101
	v_readfirstlane_b32 s100, v190
	v_and_b32_e32 v254, 63, v190
	v_lshrrev_b32_e32 v255, 6, v190
	s_lshr_b32 s100, s100, 5
	s_add_i32 s98, s98, s100
	s_cmp_lt_u32 s98, 0x8000
	s_cselect_b32 s100, s76, s78
	s_cselect_b32 s101, s77, s79
	s_cselect_b32 vcc_lo, 0, 0x8000
	s_sub_u32 vcc_lo, s98, vcc_lo
	s_lshl_b32 vcc_lo, vcc_lo, 12
	s_add_u32 s100, s100, vcc_lo
	s_addc_u32 s101, s101, 0
	v_lshlrev_b32_e32 v254, 4, v254
	v_lshlrev_b32_e32 v255, 11, v255
	v_add_u32_e32 v255, v255, v254
	v_add_u32_e32 v255, 0x20000, v255
	s_and_b32 s99, s8, 7
	s_lshl_b32 s99, s99, 3
	s_lshr_b32 vcc_lo, s8, 5
	s_add_i32 s99, s99, vcc_lo
	s_add_i32 s99, s99, 2
	ds_write_b128 v255, v[178:181]
	ds_write_b128 v255, v[154:157] offset:1024
	global_load_dwordx4 v[232:235], v254, s[100:101]
	global_load_dwordx4 v[236:239], v254, s[100:101] offset:1024
	global_load_dwordx4 v[240:243], v254, s[100:101] offset:2048
	global_load_dwordx4 v[244:247], v254, s[100:101] offset:3072
	s_add_u32 s100, s100, 0x1000
	s_addc_u32 s101, s101, 0
	global_load_dwordx4 v[182:185], v254, s[100:101]
	global_load_dwordx4 v[250:253], v254, s[100:101] offset:1024
	global_load_dwordx4 v[178:181], v254, s[100:101] offset:2048
	global_load_dwordx4 v[154:157], v254, s[100:101] offset:3072
	s_branch .Lax_issued
